# cache-policy hint: non-temporal stores for the attention O hand-off rows
# baseline (speedup 1.0000x reference)
.Latt_noprev_24:
	v_max_f32_e32 v116, v80, v35
	v_sub_f32_e32 v117, v80, v116
	v_sub_f32_e32 v118, v35, v116
	v_exp_f32_e32 v117, v117
	v_exp_f32_e32 v118, v118
	s_lshl_b32 s5, s24, 7
	v_add_u32_e32 v83, s5, v17
	v_lshlrev_b32_e32 v83, s20, v83
	v_add_u32_e32 v83, s21, v83
	v_fma_f32 v119, v36, v118, v117
	v_rcp_f32_e32 v122, v119
	v_lshl_add_u32 v123, v83, 11, v19
	s_nop 0
	v_mul_f32_e32 v120, v117, v122
	v_mul_f32_e32 v121, v118, v122
	v_lshlrev_b32_e32 v124, 16, v64
	v_and_b32_e32 v125, 0xffff0000, v64
	v_lshlrev_b32_e32 v126, 16, v65
	v_and_b32_e32 v127, 0xffff0000, v65
	v_mul_f32_e32 v124, v120, v124
	v_mul_f32_e32 v125, v120, v125
	v_mul_f32_e32 v126, v120, v126
	v_mul_f32_e32 v127, v120, v127
	v_fma_f32 v124, v228, v121, v124
	v_fma_f32 v125, v229, v121, v125
	v_fma_f32 v126, v230, v121, v126
	v_fma_f32 v127, v231, v121, v127
	v_cvt_pk_bf16_f32 v84, v124, v125
	v_cvt_pk_bf16_f32 v85, v126, v127
	v_lshlrev_b32_e32 v124, 16, v66
	v_and_b32_e32 v125, 0xffff0000, v66
	v_lshlrev_b32_e32 v126, 16, v67
	v_and_b32_e32 v127, 0xffff0000, v67
	v_mul_f32_e32 v124, v120, v124
	v_mul_f32_e32 v125, v120, v125
	v_mul_f32_e32 v126, v120, v126
	v_mul_f32_e32 v127, v120, v127
	v_fma_f32 v124, v232, v121, v124
	v_fma_f32 v125, v233, v121, v125
	v_fma_f32 v126, v234, v121, v126
	v_fma_f32 v127, v235, v121, v127
	v_cvt_pk_bf16_f32 v86, v124, v125
	v_cvt_pk_bf16_f32 v87, v126, v127
	v_lshlrev_b32_e32 v124, 16, v68
	v_and_b32_e32 v125, 0xffff0000, v68
	v_lshlrev_b32_e32 v126, 16, v69
	v_and_b32_e32 v127, 0xffff0000, v69
	v_mul_f32_e32 v124, v120, v124
	v_mul_f32_e32 v125, v120, v125
	v_mul_f32_e32 v126, v120, v126
	v_mul_f32_e32 v127, v120, v127
	v_fma_f32 v124, v236, v121, v124
	v_fma_f32 v125, v237, v121, v125
	v_fma_f32 v126, v238, v121, v126
	v_fma_f32 v127, v239, v121, v127
	v_cvt_pk_bf16_f32 v88, v124, v125
	v_cvt_pk_bf16_f32 v89, v126, v127
	v_lshlrev_b32_e32 v124, 16, v70
	v_and_b32_e32 v125, 0xffff0000, v70
	v_lshlrev_b32_e32 v126, 16, v71
	v_and_b32_e32 v127, 0xffff0000, v71
	v_mul_f32_e32 v124, v120, v124
	v_mul_f32_e32 v125, v120, v125
	v_mul_f32_e32 v126, v120, v126
	v_mul_f32_e32 v127, v120, v127
	v_fma_f32 v124, v240, v121, v124
	v_fma_f32 v125, v241, v121, v125
	v_fma_f32 v126, v242, v121, v126
	v_fma_f32 v127, v243, v121, v127
	v_cvt_pk_bf16_f32 v90, v124, v125
	v_cvt_pk_bf16_f32 v91, v126, v127
	s_nop 1
	v_permlane16_swap_b32_e32 v84, v86
	v_permlane16_swap_b32_e32 v85, v87
	v_permlane16_swap_b32_e32 v88, v90
	v_permlane16_swap_b32_e32 v89, v91
	global_store_dwordx4 v123, v[84:87], s[42:43] offset:0 nt
	global_store_dwordx4 v123, v[88:91], s[42:43] offset:64 nt
	v_log_f32_e32 v130, v119
	v_lshlrev_b32_e32 v131, 2, v83
	s_nop 0
	v_add_f32_e32 v130, v116, v130
	s_mov_b64 exec, 0xffff
	global_store_dword v131, v130, s[44:45]
	s_mov_b64 exec, -1
	s_cmp_lt_u32 s4, 16
	s_cbranch_scc1 .Latt_odummy_25
	v_lshl_add_u32 v1, v82, 11, v19
	global_load_dwordx4 v[64:67], v1, s[42:43] offset:0
	global_load_dwordx4 v[68:71], v1, s[42:43] offset:64
	v_lshlrev_b32_e32 v0, 2, v82
	global_load_dword v80, v0, s[44:45]
	s_branch .Latt_odone_26

.Latt_noprev_43:
	v_max_f32_e32 v116, v81, v35
	v_sub_f32_e32 v117, v81, v116
	v_sub_f32_e32 v118, v35, v116
	v_exp_f32_e32 v117, v117
	v_exp_f32_e32 v118, v118
	s_lshl_b32 s5, s24, 7
	v_add_u32_e32 v83, s5, v17
	v_lshlrev_b32_e32 v83, s20, v83
	v_add_u32_e32 v83, s21, v83
	v_fma_f32 v119, v36, v118, v117
	v_rcp_f32_e32 v122, v119
	v_lshl_add_u32 v123, v83, 11, v19
	s_nop 0
	v_mul_f32_e32 v120, v117, v122
	v_mul_f32_e32 v121, v118, v122
	v_lshlrev_b32_e32 v124, 16, v72
	v_and_b32_e32 v125, 0xffff0000, v72
	v_lshlrev_b32_e32 v126, 16, v73
	v_and_b32_e32 v127, 0xffff0000, v73
	v_mul_f32_e32 v124, v120, v124
	v_mul_f32_e32 v125, v120, v125
	v_mul_f32_e32 v126, v120, v126
	v_mul_f32_e32 v127, v120, v127
	v_fma_f32 v124, v228, v121, v124
	v_fma_f32 v125, v229, v121, v125
	v_fma_f32 v126, v230, v121, v126
	v_fma_f32 v127, v231, v121, v127
	v_cvt_pk_bf16_f32 v84, v124, v125
	v_cvt_pk_bf16_f32 v85, v126, v127
	v_lshlrev_b32_e32 v124, 16, v74
	v_and_b32_e32 v125, 0xffff0000, v74
	v_lshlrev_b32_e32 v126, 16, v75
	v_and_b32_e32 v127, 0xffff0000, v75
	v_mul_f32_e32 v124, v120, v124
	v_mul_f32_e32 v125, v120, v125
	v_mul_f32_e32 v126, v120, v126
	v_mul_f32_e32 v127, v120, v127
	v_fma_f32 v124, v232, v121, v124
	v_fma_f32 v125, v233, v121, v125
	v_fma_f32 v126, v234, v121, v126
	v_fma_f32 v127, v235, v121, v127
	v_cvt_pk_bf16_f32 v86, v124, v125
	v_cvt_pk_bf16_f32 v87, v126, v127
	v_lshlrev_b32_e32 v124, 16, v76
	v_and_b32_e32 v125, 0xffff0000, v76
	v_lshlrev_b32_e32 v126, 16, v77
	v_and_b32_e32 v127, 0xffff0000, v77
	v_mul_f32_e32 v124, v120, v124
	v_mul_f32_e32 v125, v120, v125
	v_mul_f32_e32 v126, v120, v126
	v_mul_f32_e32 v127, v120, v127
	v_fma_f32 v124, v236, v121, v124
	v_fma_f32 v125, v237, v121, v125
	v_fma_f32 v126, v238, v121, v126
	v_fma_f32 v127, v239, v121, v127
	v_cvt_pk_bf16_f32 v88, v124, v125
	v_cvt_pk_bf16_f32 v89, v126, v127
	v_lshlrev_b32_e32 v124, 16, v78
	v_and_b32_e32 v125, 0xffff0000, v78
	v_lshlrev_b32_e32 v126, 16, v79
	v_and_b32_e32 v127, 0xffff0000, v79
	v_mul_f32_e32 v124, v120, v124
	v_mul_f32_e32 v125, v120, v125
	v_mul_f32_e32 v126, v120, v126
	v_mul_f32_e32 v127, v120, v127
	v_fma_f32 v124, v240, v121, v124
	v_fma_f32 v125, v241, v121, v125
	v_fma_f32 v126, v242, v121, v126
	v_fma_f32 v127, v243, v121, v127
	v_cvt_pk_bf16_f32 v90, v124, v125
	v_cvt_pk_bf16_f32 v91, v126, v127
	s_nop 1
	v_permlane16_swap_b32_e32 v84, v86
	v_permlane16_swap_b32_e32 v85, v87
	v_permlane16_swap_b32_e32 v88, v90
	v_permlane16_swap_b32_e32 v89, v91
	global_store_dwordx4 v123, v[84:87], s[42:43] offset:0 nt
	global_store_dwordx4 v123, v[88:91], s[42:43] offset:64 nt
	v_log_f32_e32 v130, v119
	v_lshlrev_b32_e32 v131, 2, v83
	s_nop 0
	v_add_f32_e32 v130, v116, v130
	s_mov_b64 exec, 0xffff
	global_store_dword v131, v130, s[44:45]
	s_mov_b64 exec, -1
	s_cmp_lt_u32 s4, 16
	s_cbranch_scc1 .Latt_odummy_44
	v_lshl_add_u32 v1, v82, 11, v19
	global_load_dwordx4 v[72:75], v1, s[42:43] offset:0
	global_load_dwordx4 v[76:79], v1, s[42:43] offset:64
	v_lshlrev_b32_e32 v0, 2, v82
	global_load_dword v81, v0, s[44:45]
	s_branch .Latt_odone_45
